# group-local seams 1 and 2 too (P2 unit remap, conversion WGs arrive early, FLUSH3 write-back for converted weights)
# speedup vs baseline: 1.0246x; 1.0018x over previous
; #define LAS __attribute__((address_space(3)))
; __device__ __forceinline__ unsigned xb_ld(unsigned* p) { return __hip_atomic_load(p, __ATOMIC_RELAXED, __HIP_MEMORY_SCOPE_AGENT); }
; __device__ __forceinline__ unsigned xb_add(unsigned* p, unsigned v) { return __hip_atomic_fetch_add(p, v, __ATOMIC_RELAXED, __HIP_MEMORY_SCOPE_AGENT); }
; __device__ __forceinline__ unsigned xb_xcc_id() { return (unsigned)__builtin_amdgcn_s_getreg((3 << 11) | 20) & 0xFu; }
; __device__ __forceinline__ void grid_barrier(unsigned* barw, int k, volatile LAS unsigned* st) {
;     asm volatile("s_waitcnt vmcnt(0)" ::: "memory");
;     __syncthreads();
;     if (threadIdx.x == 0) {
;         __builtin_amdgcn_s_waitcnt(0);
;         const unsigned x = xb_xcc_id();
;         unsigned nloc = st[0], nx = st[1];
;         if (nloc == 0u) {
;             const unsigned G = gridDim.x;
;             for (;;) { unsigned sum = 0u, cnt = 0u, mine = 0u;
; #pragma unroll
;                 for (unsigned j = 0; j < 16; ++j) { const unsigned c = xb_ld(barw + 64 * j); sum += c; cnt += (c > 0u) ? 1u : 0u; mine = (j == x) ? c : mine; }
;                 if (sum == G) { nloc = mine; nx = cnt; break; }
;                 __builtin_amdgcn_s_sleep(1); }
;             st[0] = nloc; st[1] = nx;
;         }
;         unsigned* sb = barw + 1024 + k * 2304;
;         const unsigned old = xb_add(sb + 64 * x, 1u);
;         if (old + 1u == nloc) {
;             __builtin_amdgcn_fence(__ATOMIC_RELEASE, "agent");
;             asm volatile("s_waitcnt vmcnt(0)" ::: "memory");
;             const unsigned og = xb_add(sb + 2048, 1u);
;             if (og + 1u == nx) xb_add(sb + 2112, 1u);
;             else while (xb_ld(sb + 2112) == 0u) __builtin_amdgcn_s_sleep(1);
;             __builtin_amdgcn_fence(__ATOMIC_ACQUIRE, "agent");
;             xb_add(sb + 1024 + 64 * x, 1u);
;             asm volatile("s_waitcnt vmcnt(0)" ::: "memory");
;         } else {
;             while (xb_ld(sb + 1024 + 64 * x) == 0u) __builtin_amdgcn_s_sleep(1);
;             __builtin_amdgcn_fence(__ATOMIC_ACQUIRE, "agent");
;             asm volatile("s_waitcnt vmcnt(0)" ::: "memory");
;         }
;     }
;     __syncthreads();
; }
.LBB0_116:
	v_readlane_b32 s0, v254, 0
	v_readlane_b32 s1, v254, 1
	s_cmp_gt_i32 s1, 1
	s_cselect_b64 s[72:73], -1, 0
	s_and_b64 s[0:1], s[4:5], s[72:73]
	s_andn2_b64 vcc, exec, s[0:1]
	s_cbranch_vccnz .LBB0_145
	s_waitcnt vmcnt(0)
	s_waitcnt lgkmcnt(0)
	s_barrier
	s_mov_b64 s[74:75], exec
	v_readlane_b32 s0, v254, 2
	v_readlane_b32 s1, v254, 3
	s_and_b64 s[0:1], s[74:75], s[0:1]
	s_mov_b64 exec, s[0:1]
	s_cbranch_execz .LBB0_144
	v_readlane_b32 s4, v254, 6
	v_readlane_b32 s5, v254, 7
	s_and_b32 s0, s70, 7
	s_lshl_b32 s0, s0, 8
	s_add_i32 s0, s0, 0x12440
	s_add_u32 s4, s4, s0
	s_addc_u32 s5, s5, 0
	s_getreg_b32 s1, hwreg(HW_REG_XCC_ID, 0, 4)
	s_lshl_b32 s1, 1, s1
	v_mov_b32_e32 v0, 0
	v_mov_b32_e32 v1, s1
	global_atomic_or v2, v0, v1, s[4:5] sc0
	s_waitcnt vmcnt(0)
	s_add_i32 s1, 0, 0x23fc0
	v_mov_b32_e32 v0, s1
	s_waitcnt vmcnt(0) expcnt(0) lgkmcnt(0)
	s_getreg_b32 s0, hwreg(HW_REG_XCC_ID, 0, 4)
	ds_read_b32 v1, v0
	s_add_i32 s1, 0, 0x23fc4
	v_mov_b32_e32 v0, s1
	ds_read_b32 v0, v0
	s_and_b32 s14, s0, 15
	s_waitcnt lgkmcnt(1)
	v_cmp_ne_u32_e32 vcc, 0, v1
	s_cbranch_vccnz .LBB0_124
	s_cmp_eq_u32 s14, 0
	s_cselect_b64 s[2:3], -1, 0
	s_cmp_eq_u32 s14, 1
	s_cselect_b64 s[4:5], -1, 0
	s_cmp_eq_u32 s14, 2
	s_cselect_b64 s[6:7], -1, 0
	s_cmp_eq_u32 s14, 3
	s_cselect_b64 s[8:9], -1, 0
	s_cmp_eq_u32 s14, 4
	s_cselect_b64 s[10:11], -1, 0
	s_cmp_eq_u32 s14, 5
	s_cselect_b64 s[12:13], -1, 0
	s_cmp_eq_u32 s14, 6
	s_cselect_b64 s[0:1], -1, 0
	s_cmp_eq_u32 s14, 7
	s_cselect_b64 s[16:17], -1, 0
	s_cmp_eq_u32 s14, 8
	s_cselect_b64 s[18:19], -1, 0
	s_cmp_eq_u32 s14, 9
	s_cselect_b64 s[20:21], -1, 0
	s_cmp_eq_u32 s14, 10
	s_cselect_b64 s[22:23], -1, 0
	s_cmp_eq_u32 s14, 11
	s_cselect_b64 s[24:25], -1, 0
	s_cmp_eq_u32 s14, 12
	s_cselect_b64 s[26:27], -1, 0
	s_cmp_eq_u32 s14, 13
	s_cselect_b64 s[28:29], -1, 0
	s_cmp_eq_u32 s14, 14
	s_cselect_b64 s[30:31], -1, 0
	s_cmp_eq_u32 s14, 15
	s_cselect_b64 s[34:35], -1, 0
	v_mov_b32_e32 v2, 0
	v_mov_b32_e32 v1, 0
	s_branch .LBB0_121

; __device__ __forceinline__ void grid_barrier(unsigned* barw, int k, volatile LAS unsigned* st) {
;     ...
;             asm volatile("s_waitcnt vmcnt(0)" ::: "memory");
;         }
;     }
;     __syncthreads();
; }
.LBB0_144:
	s_or_b64 exec, exec, s[74:75]
	s_mov_b64 s[2:3], exec
	v_readlane_b32 s0, v254, 2
	v_readlane_b32 s1, v254, 3
	s_and_b64 s[0:1], s[2:3], s[0:1]
	s_mov_b64 exec, s[0:1]
	s_cbranch_execz .Lflag_skip
	v_readlane_b32 s4, v254, 6
	v_readlane_b32 s5, v254, 7
	s_and_b32 s0, s70, 7
	s_lshl_b32 s0, s0, 8
	s_add_i32 s0, s0, 0x12440
	s_add_u32 s4, s4, s0
	s_addc_u32 s5, s5, 0
	v_mov_b32_e32 v0, 0
	global_load_dword v2, v0, s[4:5] sc1
	s_waitcnt vmcnt(0)
	v_readfirstlane_b32 s7, v2
	s_bcnt1_i32_b32 s7, s7
	s_cmp_eq_u32 s7, 1
	s_cselect_b32 s7, 1, 0
	v_mov_b32_e32 v0, 0x23fc8
	v_mov_b32_e32 v1, s7
	ds_write_b32 v0, v1
.Lflag_skip:
	s_mov_b64 exec, s[2:3]
	s_waitcnt lgkmcnt(0)
	s_barrier

; #define LAS __attribute__((address_space(3)))
; __device__ __forceinline__ unsigned xb_ld(unsigned* p) { return __hip_atomic_load(p, __ATOMIC_RELAXED, __HIP_MEMORY_SCOPE_AGENT); }
; __device__ __forceinline__ unsigned xb_add(unsigned* p, unsigned v) { return __hip_atomic_fetch_add(p, v, __ATOMIC_RELAXED, __HIP_MEMORY_SCOPE_AGENT); }
; __device__ __forceinline__ unsigned xb_xcc_id() { return (unsigned)__builtin_amdgcn_s_getreg((3 << 11) | 20) & 0xFu; }
; __device__ __forceinline__ void grid_barrier(unsigned* barw, int k, volatile LAS unsigned* st) {
;     asm volatile("s_waitcnt vmcnt(0)" ::: "memory");
;     __syncthreads();
;     if (threadIdx.x == 0) {
;         __builtin_amdgcn_s_waitcnt(0);
;         const unsigned x = xb_xcc_id();
;         unsigned nloc = st[0], nx = st[1];
;         if (nloc == 0u) {
;             const unsigned G = gridDim.x;
;             for (;;) { unsigned sum = 0u, cnt = 0u, mine = 0u;
; #pragma unroll
;                 for (unsigned j = 0; j < 16; ++j) { const unsigned c = xb_ld(barw + 64 * j); sum += c; cnt += (c > 0u) ? 1u : 0u; mine = (j == x) ? c : mine; }
;                 if (sum == G) { nloc = mine; nx = cnt; break; }
;                 __builtin_amdgcn_s_sleep(1); }
;             st[0] = nloc; st[1] = nx;
;         }
;         unsigned* sb = barw + 1024 + k * 2304;
;         const unsigned old = xb_add(sb + 64 * x, 1u);
;         if (old + 1u == nloc) {
;             __builtin_amdgcn_fence(__ATOMIC_RELEASE, "agent");
;             asm volatile("s_waitcnt vmcnt(0)" ::: "memory");
;             const unsigned og = xb_add(sb + 2048, 1u);
;             if (og + 1u == nx) xb_add(sb + 2112, 1u);
;             else while (xb_ld(sb + 2112) == 0u) __builtin_amdgcn_s_sleep(1);
;             __builtin_amdgcn_fence(__ATOMIC_ACQUIRE, "agent");
;             xb_add(sb + 1024 + 64 * x, 1u);
;             asm volatile("s_waitcnt vmcnt(0)" ::: "memory");
;         } else {
;             while (xb_ld(sb + 1024 + 64 * x) == 0u) __builtin_amdgcn_s_sleep(1);
;             __builtin_amdgcn_fence(__ATOMIC_ACQUIRE, "agent");
;             asm volatile("s_waitcnt vmcnt(0)" ::: "memory");
;         }
;     }
;     __syncthreads();
; }
.LBB0_429:
	v_readlane_b32 s0, v254, 0
	v_readlane_b32 s1, v254, 1
	s_cmp_gt_i32 s1, 2
	s_cselect_b64 s[72:73], -1, 0
	s_and_b64 s[0:1], s[10:11], s[72:73]
	v_readlane_b32 s76, v254, 4
	s_andn2_b64 vcc, exec, s[0:1]
	v_readlane_b32 s77, v254, 5
	v_readlane_b32 s78, v254, 6
	v_readlane_b32 s79, v254, 7
	s_cbranch_vccnz .LBB0_458
	s_waitcnt vmcnt(0)
	s_waitcnt vmcnt(0) lgkmcnt(0)
	s_barrier
	s_mov_b64 s[74:75], exec
	v_readlane_b32 s0, v254, 2
	v_readlane_b32 s1, v254, 3
	s_and_b64 s[0:1], s[74:75], s[0:1]
	s_mov_b64 exec, s[0:1]
	s_cbranch_execz .LBB0_457
	s_cmp_lg_u32 s88, 0x100
	s_cbranch_scc1 .Lgb4_orig
	v_mov_b32_e32 v2, 0x23fc8
	ds_read_b32 v2, v2
	s_waitcnt vmcnt(0) lgkmcnt(0)
	v_readfirstlane_b32 s9, v2
	s_cmp_eq_u32 s9, 1
	s_cbranch_scc1 .Lgb4_norel
	buffer_wbl2 sc1
	s_waitcnt vmcnt(0)
.Lgb4_norel:
	v_readlane_b32 s4, v254, 6
	v_readlane_b32 s5, v254, 7
	s_and_b32 s0, s70, 7
	s_lshl_b32 s0, s0, 8
	s_add_i32 s0, s0, 0x10cc0
	s_add_u32 s4, s4, s0
	s_addc_u32 s5, s5, 0
	s_lshr_b32 s6, s88, 3
	v_mov_b32_e32 v0, 0
	v_mov_b32_e32 v1, 1
	global_atomic_add v0, v1, s[4:5]
	s_cmpk_lt_i32 s70, 0x80
	s_cbranch_scc1 .Lgb4_spin
	s_add_u32 s4, s4, 0x800
	s_addc_u32 s5, s5, 0
	global_atomic_add v0, v1, s[4:5]
	s_waitcnt vmcnt(0)
	s_branch .LBB0_457
.Lgb4_spin:
	global_load_dword v2, v0, s[4:5] sc1
	s_waitcnt vmcnt(0)
	v_readfirstlane_b32 s7, v2
	s_cmp_ge_u32 s7, s6
	s_cbranch_scc1 .Lgb4_acq
	s_sleep 1
	s_branch .Lgb4_spin

; #define PG8_LAS __attribute__((address_space(3)))
; #define PG8_STAGE(bufoff, gbase, voff) do { _Pragma("unroll") for (int _i = 0; _i < 2; ++_i) \
;         __builtin_amdgcn_global_load_lds((const unsigned*)((const char*)(gbase) + (voff)[_i]), (PG8_LAS unsigned*)(lds + (bufoff) + ldsw + _i * 8192), 16, 0, 0); } while (0)
; #define PG8_WAIT_V(n) asm volatile("s_waitcnt vmcnt(" #n ")" ::: "memory")
; #define PG8_BAR __builtin_amdgcn_s_barrier()
; __device__ __forceinline__ unsigned cvt_pk_bf16(float lo, float hi) { unsigned r; asm volatile("v_cvt_pk_bf16_f32 %0, %1, %2" : "=v"(r) : "v"(lo), "v"(hi)); return r; }
; template <class Epi, class Sched, bool ALIGN_EPI = false, bool SP2 = false>
; __device__ __forceinline__ void gemm_phase(PG8_LAS unsigned char* lds, const Gemm g, const Sched& S, const Epi& E) {
;     const int tid = threadIdx.x, wid = __builtin_amdgcn_readfirstlane(tid >> 6), lane = tid & 63, wr = wid >> 2, wc = wid & 3, fr = lane & 15, fq = lane >> 4;
;     const int K = g.K, nt = K / BK, lda = g.lda, ldb = g.ldb;
;     unsigned voffA[2], voffB[2];
; #pragma unroll
;     for (int i = 0; i < 2; ++i) { int R, C; stage_rc(tid * 16 + i * 8192, R, C); const int Rb = Epi::PERM ? ((R & ~31) + perm32(R & 31)) : R;
;         voffA[i] = (unsigned)(R * lda + C) * 2u; voffB[i] = (unsigned)(Rb * ldb + C) * 2u; }
;     const size_t kstep = (size_t)(BK * 2);
;     const size_t hstepA = (size_t)HALF * lda * 2, hstepB = (size_t)HALF * ldb * 2;
;     const size_t tstepA = 2 * hstepA, tstepB = 2 * hstepB;
;     const unsigned ldsw = (unsigned)wid * 1024u;
;     const int aoff = lds_byte(wr * 64 + fr, fq * 8), boff = lds_byte(wc * 32 + fr, fq * 8);
;     ...
;     const char* cA = (const char*)g.A + (size_t)cur.pm * tstepA + cur.koff; const char* cB = (const char*)g.Bt + (size_t)cur.pn * tstepB + cur.koff;
;     S.a_ready(cur);
;     if constexpr (SP2) {
;         PG8_STAGE(PG8_SB(0, 0), cB, voffB); PG8_STAGE(PG8_SB(0, 1), cB + hstepB, voffB); PG8_STAGE(PG8_SA(0, 0), cA, voffA); PG8_STAGE(PG8_SA(0, 1), cA + hstepA, voffA);
;         if (wr == 1) PG8_BAR;
;         PG8_WAIT_V(2); PG8_BAR;
;         PG8_STAGE(PG8_SB(1, 0), cB + kstep, voffB); PG8_STAGE(PG8_SA(1, 0), cA + kstep, voffA); PG8_STAGE(PG8_SB(1, 1), cB + hstepB + kstep, voffB);
;         PG8_WAIT_V(6); PG8_BAR;
.LBB0_465:
	s_cmpk_gt_i32 s70, 0x7f
	v_readfirstlane_b32 s14, v184
	s_cbranch_scc1 .LBB0_475
	s_mov_b32 s99, s70
	s_cmp_lg_u32 s88, 0x100
	s_cbranch_scc1 .Lp2_nomap
	s_lshr_b32 s0, s70, 3
	s_and_b32 s1, s70, 7
	s_lshl_b32 s1, s1, 1
	s_and_b32 s99, s0, 1
	s_or_b32 s99, s99, s1
	s_bfe_u32 s1, s0, 0x10001
	s_lshl_b32 s1, s1, 4
	s_or_b32 s99, s99, s1
	s_lshr_b32 s1, s0, 2
	s_lshl_b32 s1, s1, 5
	s_or_b32 s99, s99, s1
.Lp2_nomap:
	v_lshrrev_b32_e32 v0, 5, v184
	v_lshrrev_b32_e32 v2, 1, v184
	v_and_b32_e32 v0, 4, v0
	v_bfe_u32 v1, v184, 2, 2
	v_and_b32_e32 v11, 24, v2
	v_or3_b32 v0, v0, v1, v11
	v_lshlrev_b32_e32 v1, 4, v184
	s_lshl_b32 s6, s99, 5
	v_add_u32_e32 v8, 0x2000, v1
	s_lshr_b32 s1, s14, 6
	s_and_b32 s24, s6, 0xfffffc00
	v_lshrrev_b32_e32 v2, 7, v8
	s_movk_i32 s6, 0xe0
	v_and_b32_e32 v4, 32, v184
	s_lshr_b32 s0, s14, 8
	s_lshl_b32 s15, s1, 10
	s_and_b32 s23, s99, 31
	v_and_or_b32 v3, v2, s6, v0
	v_bitop3_b32 v9, v1, v4, 48 bitop3:0x6c
	v_and_b32_e32 v10, 64, v184
	v_bfe_u32 v12, v184, 2, 4
	s_movk_i32 s6, 0xf0
	s_add_u32 s18, s78, 0xe600000
	v_or_b32_e32 v1, v9, v10
	v_and_or_b32 v2, v2, s6, v12
	s_addc_u32 s19, s79, 0
	v_lshl_or_b32 v130, v2, 11, v1
	v_lshrrev_b32_e32 v2, 3, v184
	s_movk_i32 s6, 0x60
	s_add_u32 s20, s78, 0x1800000
	v_and_or_b32 v0, v2, s6, v0
	s_movk_i32 s6, 0x70
	s_addc_u32 s21, s79, 0
	v_lshl_or_b32 v132, v0, 12, v1
	v_and_or_b32 v0, v2, s6, v12
	s_lshl_b32 s6, s99, 16
	s_lshl_b32 s8, s23, 19
	s_ashr_i32 s10, s24, 31
	s_and_b32 s6, s6, 0x100000
	s_add_u32 s6, s20, s6
	s_addc_u32 s7, s21, 0
	s_add_u32 s6, s6, s24
	s_addc_u32 s7, s7, s10
	s_add_i32 s22, s15, 0
	s_add_i32 m0, s22, 0x10000
	v_lshl_or_b32 v128, v3, 12, v1
	global_load_lds_dwordx4 v132, s[6:7]
	s_add_i32 m0, s22, 0x12000
	s_add_u32 s11, s18, s8
	s_addc_u32 s12, s19, 0
	s_add_u32 s8, s6, 0x80000
	global_load_lds_dwordx4 v128, s[6:7]
	s_addc_u32 s9, s7, 0
	s_add_i32 m0, s22, 0x14000
	v_lshl_or_b32 v134, v0, 11, v1
	global_load_lds_dwordx4 v132, s[8:9]
	s_add_i32 m0, s22, 0x16000
	v_mov_b32_e32 v137, 0
	global_load_lds_dwordx4 v128, s[8:9]
	s_add_u32 s8, s11, s24
	s_addc_u32 s9, s12, s10
	s_add_i32 s25, s22, 0x2000
	s_mov_b32 m0, s22
	s_add_u32 s10, s8, 0x40000
	global_load_lds_dwordx4 v134, s[8:9]
	s_mov_b32 m0, s25
	s_addc_u32 s11, s9, 0
	s_add_i32 s26, s22, 0x4000
	global_load_lds_dwordx4 v130, s[8:9]
	s_mov_b32 m0, s26
	s_add_i32 s27, s22, 0x6000
	global_load_lds_dwordx4 v134, s[10:11]
	s_mov_b32 m0, s27
	v_mov_b32_e32 v133, v137
	global_load_lds_dwordx4 v130, s[10:11]
	v_mov_b32_e32 v129, v137
	v_mov_b32_e32 v135, v137
	v_mov_b32_e32 v131, v137
	s_mov_b32 s28, 0
	v_lshl_add_u64 v[6:7], s[6:7], 0, v[132:133]
	v_lshl_add_u64 v[4:5], s[6:7], 0, v[128:129]
	v_lshl_add_u64 v[2:3], s[8:9], 0, v[134:135]
	s_cmp_lg_u32 s0, 1
	v_lshl_add_u64 v[0:1], s[8:9], 0, v[130:131]
	s_cbranch_scc1 .LBB0_468
	s_barrier
.LBB0_468:
	s_lshl_b32 s1, s1, 5
	s_mov_b64 s[10:11], 0x80
	s_and_b32 s1, s1, 0x60
	s_add_i32 m0, s22, 0x18000
	v_lshl_add_u64 v[6:7], v[6:7], 0, s[10:11]
	s_lshl_b32 s16, s0, 13
	s_lshl_b32 s17, s1, 7
	s_ashr_i32 s29, s99, 31
	s_waitcnt vmcnt(2)
	s_barrier
	global_load_lds_dwordx4 v[6:7], off
	v_lshl_add_u64 v[4:5], v[4:5], 0, s[10:11]
	s_add_i32 m0, s22, 0x1a000
	s_add_i32 s30, s22, 0x8000
	s_add_i32 s31, s22, 0xa000
	global_load_lds_dwordx4 v[4:5], off
	v_lshl_add_u64 v[2:3], v[2:3], 0, s[10:11]
	s_mov_b32 m0, s30
	s_add_u32 s12, s6, 0x80080
	global_load_lds_dwordx4 v[2:3], off
	v_lshl_add_u64 v[0:1], v[0:1], 0, s[10:11]
	s_mov_b32 m0, s31
	s_addc_u32 s13, s7, 0
	global_load_lds_dwordx4 v[0:1], off
	s_add_i32 m0, s22, 0x1c000
	v_lshl_add_u64 v[0:1], s[12:13], 0, v[132:133]
	global_load_lds_dwordx4 v[0:1], off
	v_lshl_add_u64 v[0:1], s[12:13], 0, v[128:129]
	s_add_i32 m0, s22, 0x1e000
	v_lshlrev_b32_e32 v2, 2, v184
	global_load_lds_dwordx4 v[0:1], off
	v_and_b32_e32 v0, 15, v184
	v_lshlrev_b32_e32 v1, 1, v11
	v_lshl_or_b32 v148, s0, 6, v0
	v_lshl_or_b32 v0, v0, 6, v1
	v_and_b32_e32 v2, 32, v2
	v_bitop3_b32 v3, v0, s16, v2 bitop3:0xde
	v_lshlrev_b32_e32 v0, 6, v184
	s_movk_i32 s0, 0x3c0
	v_and_or_b32 v0, v0, s0, v1
	s_lshl_b32 s0, s1, 2
	s_add_u32 s0, s78, s0
	s_addc_u32 s1, s79, 0
	v_lshlrev_b32_e32 v136, 2, v11
	v_bitop3_b32 v150, s17, v0, v2 bitop3:0xf6
	v_lshl_add_u64 v[0:1], s[0:1], 0, v[136:137]
	s_mov_b64 s[0:1], 0x2600000
	v_lshl_add_u64 v[138:139], v[0:1], 0, s[0:1]
	v_lshlrev_b32_e32 v0, 8, v184
	v_and_b32_e32 v0, 0x38000, v0
	v_lshlrev_b32_e32 v1, 11, v12
	v_or3_b32 v0, v9, v0, v1
	v_add_u32_e32 v140, v0, v10
	v_lshlrev_b32_e32 v0, 4, v8
	s_waitcnt vmcnt(6)
	v_and_b32_e32 v0, 0x78000, v0
	v_or3_b32 v0, v9, v0, v1
	s_add_i32 s33, 0, 0x10000
	s_add_i32 s34, 0, 0x14000
	v_or_b32_e32 v152, 16, v148
	v_or_b32_e32 v153, 32, v148
	v_or_b32_e32 v154, 48, v148
	v_mov_b32_e32 v141, v137
	v_add_u32_e32 v142, v0, v10
	v_mov_b32_e32 v143, v137
	v_mov_b64_e32 v[144:145], 0x7f
	v_mov_b64_e32 v[146:147], 0x80
	v_add_u32_e32 v155, s33, v150
	v_add_u32_e32 v156, s34, v150
	v_add_u32_e32 v157, 0, v3
	s_barrier
;     __device__ bool next(int i, Unit& u) const { const long L = (long)i * G + c; if (L >= 128) return false; u.pm = (int)L & 31; u.pn = u.pm >> 4; u.koff = ((int)L >> 5) * 1024; return true; }
; template <class Epi, class Sched, bool ALIGN_EPI = false, bool SP2 = false>
; __device__ __forceinline__ void gemm_phase(PG8_LAS unsigned char* lds, const Gemm g, const Sched& S, const Epi& E) {
;     ...
;     for (;;) {
;         const bool has_next = S.next(ui + 1, nxt);
;         const char* nA = has_next ? (const char*)g.A + (size_t)nxt.pm * tstepA + nxt.koff : cA; const char* nB = has_next ? (const char*)g.Bt + (size_t)nxt.pn * tstepB + nxt.koff : cB;
;     ...
; #pragma unroll
;         for (int a = 0; a < 2; ++a)
; #pragma unroll
;             for (int b = 0; b < 2; ++b)
; #pragma unroll
;                 for (int m = 0; m < 4; ++m)
; #pragma unroll
;                     for (int n = 0; n < 2; ++n) acc[a][b][m][n] = (f32x4){0.f, 0.f, 0.f, 0.f};
;         cur = nxt; cA = nA; cB = nB; ++ui;
.LBB0_469:
	s_add_i32 s28, s28, 1
	s_mul_i32 s0, s5, s28
	s_mul_hi_u32 s1, s4, s28
	s_add_i32 s1, s1, s0
	s_mul_i32 s0, s4, s28
	s_mov_b64 s[16:17], s[6:7]
	s_add_u32 s6, s0, s99
	s_addc_u32 s7, s1, s29
	v_cmp_gt_i64_e32 vcc, s[6:7], v[144:145]
	v_cmp_lt_i64_e64 s[0:1], s[6:7], v[146:147]
	s_lshl_b32 s7, s6, 5
	s_mov_b64 s[12:13], s[8:9]
	s_mov_b32 s8, s37
	s_mov_b32 s9, s36
	s_mov_b32 s38, s35
	s_and_b32 s35, s7, 0xfffffc00
	s_and_b32 s37, s6, 31
	s_bfe_u32 s36, s6, 0x10004
	s_and_b64 s[6:7], s[0:1], exec
	s_cselect_b32 s8, s37, s8
	s_cselect_b32 s40, s35, s38
	s_cselect_b32 s6, s36, s9
	s_ashr_i32 s9, s8, 31
	s_lshl_b64 s[8:9], s[8:9], 19
	s_add_u32 s7, s18, s8
	s_addc_u32 s9, s19, s9
	s_ashr_i32 s41, s40, 31
	s_add_u32 s8, s7, s40
	s_addc_u32 s9, s9, s41
	s_and_b64 s[38:39], s[0:1], exec
	s_cselect_b32 s38, s9, s13
	s_cselect_b32 s39, s8, s12
	s_ashr_i32 s7, s6, 31
	s_lshl_b64 s[6:7], s[6:7], 20
	s_add_u32 s6, s20, s6
	s_addc_u32 s7, s21, s7
	s_add_u32 s6, s6, s40
	s_addc_u32 s7, s7, s41
	s_and_b64 s[0:1], s[0:1], exec
	s_cselect_b32 s40, s7, s17
	s_cselect_b32 s41, s6, s16
	s_add_u32 s0, s12, 0x40080
	s_addc_u32 s1, s13, 0
	s_add_u32 s42, s16, 0x100
	v_mov_b32_e32 v0, 0
	s_addc_u32 s43, s17, 0
	s_mov_b32 s44, -2
	v_mov_b32_e32 v1, v0
	v_mov_b32_e32 v2, v0
	v_mov_b32_e32 v3, v0
	v_mov_b32_e32 v4, v0
	v_mov_b32_e32 v5, v0
	v_mov_b32_e32 v6, v0
	v_mov_b32_e32 v7, v0
	v_mov_b32_e32 v8, v0
	v_mov_b32_e32 v9, v0
	v_mov_b32_e32 v10, v0
	v_mov_b32_e32 v11, v0
	v_mov_b32_e32 v12, v0
	v_mov_b32_e32 v13, v0
	v_mov_b32_e32 v14, v0
	v_mov_b32_e32 v15, v0
	v_mov_b32_e32 v16, v0
	v_mov_b32_e32 v17, v0
	v_mov_b32_e32 v18, v0
	v_mov_b32_e32 v19, v0
	v_mov_b32_e32 v24, v0
	v_mov_b32_e32 v25, v0
	v_mov_b32_e32 v26, v0
	v_mov_b32_e32 v27, v0
	v_mov_b32_e32 v32, v0
	v_mov_b32_e32 v33, v0
	v_mov_b32_e32 v34, v0
	v_mov_b32_e32 v35, v0
	v_mov_b32_e32 v40, v0
	s_waitcnt lgkmcnt(0)
	v_mov_b32_e32 v41, v0
	v_mov_b32_e32 v42, v0
	v_mov_b32_e32 v43, v0
	v_mov_b32_e32 v20, v0
	v_mov_b32_e32 v21, v0
	v_mov_b32_e32 v22, v0
	v_mov_b32_e32 v23, v0
	v_mov_b32_e32 v28, v0
	v_mov_b32_e32 v29, v0
	v_mov_b32_e32 v30, v0
	v_mov_b32_e32 v31, v0
	v_mov_b32_e32 v36, v0
	v_mov_b32_e32 v37, v0
	v_mov_b32_e32 v38, v0
	v_mov_b32_e32 v39, v0
	v_mov_b32_e32 v44, v0
	v_mov_b32_e32 v45, v0
	v_mov_b32_e32 v46, v0
	v_mov_b32_e32 v47, v0
	v_mov_b32_e32 v48, v0
	v_mov_b32_e32 v49, v0
	v_mov_b32_e32 v50, v0
	v_mov_b32_e32 v51, v0
	v_mov_b32_e32 v52, v0
	v_mov_b32_e32 v53, v0
	v_mov_b32_e32 v54, v0
	v_mov_b32_e32 v55, v0
	v_mov_b32_e32 v56, v0
	v_mov_b32_e32 v57, v0
	v_mov_b32_e32 v58, v0
	v_mov_b32_e32 v59, v0
	v_mov_b32_e32 v60, v0
	v_mov_b32_e32 v61, v0
	v_mov_b32_e32 v62, v0
	v_mov_b32_e32 v63, v0
	v_mov_b32_e32 v64, v0
	v_mov_b32_e32 v65, v0
	v_mov_b32_e32 v66, v0
	v_mov_b32_e32 v67, v0
	v_mov_b32_e32 v68, v0
	v_mov_b32_e32 v69, v0
	v_mov_b32_e32 v70, v0
	v_mov_b32_e32 v71, v0
	v_mov_b32_e32 v72, v0
	v_mov_b32_e32 v73, v0
	v_mov_b32_e32 v74, v0
	v_mov_b32_e32 v75, v0
	v_mov_b32_e32 v76, v0
	v_mov_b32_e32 v77, v0
	v_mov_b32_e32 v78, v0
	v_mov_b32_e32 v79, v0
	v_mov_b32_e32 v80, v0
	v_mov_b32_e32 v81, v0
	v_mov_b32_e32 v82, v0
	v_mov_b32_e32 v83, v0
	v_mov_b32_e32 v88, v0
	v_mov_b32_e32 v89, v0
	v_mov_b32_e32 v90, v0
	v_mov_b32_e32 v91, v0
	v_mov_b32_e32 v96, v0
	v_mov_b32_e32 v97, v0
	v_mov_b32_e32 v98, v0
	v_mov_b32_e32 v99, v0
	v_mov_b32_e32 v104, v0
	v_mov_b32_e32 v105, v0
	v_mov_b32_e32 v106, v0
	v_mov_b32_e32 v107, v0
	v_mov_b32_e32 v84, v0
	v_mov_b32_e32 v85, v0
	v_mov_b32_e32 v86, v0
	v_mov_b32_e32 v87, v0
	v_mov_b32_e32 v92, v0
	v_mov_b32_e32 v93, v0
	v_mov_b32_e32 v94, v0
	v_mov_b32_e32 v95, v0
	v_mov_b32_e32 v100, v0
	v_mov_b32_e32 v101, v0
	v_mov_b32_e32 v102, v0
	v_mov_b32_e32 v103, v0
	v_mov_b32_e32 v108, v0
	v_mov_b32_e32 v109, v0
	v_mov_b32_e32 v110, v0
	v_mov_b32_e32 v111, v0
	v_mov_b32_e32 v112, v0
	v_mov_b32_e32 v113, v0
	v_mov_b32_e32 v114, v0
	v_mov_b32_e32 v115, v0
	v_mov_b32_e32 v116, v0
	v_mov_b32_e32 v117, v0
	v_mov_b32_e32 v118, v0
	v_mov_b32_e32 v119, v0
	v_mov_b32_e32 v120, v0
	v_mov_b32_e32 v121, v0
	v_mov_b32_e32 v122, v0
	v_mov_b32_e32 v123, v0
	v_mov_b32_e32 v124, v0
	v_mov_b32_e32 v125, v0
	v_mov_b32_e32 v126, v0
	v_mov_b32_e32 v127, v0

; #define LAS __attribute__((address_space(3)))
; __device__ __forceinline__ unsigned xb_ld(unsigned* p) { return __hip_atomic_load(p, __ATOMIC_RELAXED, __HIP_MEMORY_SCOPE_AGENT); }
; __device__ __forceinline__ unsigned xb_add(unsigned* p, unsigned v) { return __hip_atomic_fetch_add(p, v, __ATOMIC_RELAXED, __HIP_MEMORY_SCOPE_AGENT); }
; __device__ __forceinline__ unsigned xb_xcc_id() { return (unsigned)__builtin_amdgcn_s_getreg((3 << 11) | 20) & 0xFu; }
; __device__ __forceinline__ void grid_barrier(unsigned* barw, int k, volatile LAS unsigned* st) {
;     asm volatile("s_waitcnt vmcnt(0)" ::: "memory");
;     __syncthreads();
;     if (threadIdx.x == 0) {
;         __builtin_amdgcn_s_waitcnt(0);
;         const unsigned x = xb_xcc_id();
;         unsigned nloc = st[0], nx = st[1];
;         if (nloc == 0u) {
;             const unsigned G = gridDim.x;
;             for (;;) { unsigned sum = 0u, cnt = 0u, mine = 0u;
; #pragma unroll
;                 for (unsigned j = 0; j < 16; ++j) { const unsigned c = xb_ld(barw + 64 * j); sum += c; cnt += (c > 0u) ? 1u : 0u; mine = (j == x) ? c : mine; }
;                 if (sum == G) { nloc = mine; nx = cnt; break; }
;                 __builtin_amdgcn_s_sleep(1); }
;             st[0] = nloc; st[1] = nx;
;         }
;         unsigned* sb = barw + 1024 + k * 2304;
;         const unsigned old = xb_add(sb + 64 * x, 1u);
;         if (old + 1u == nloc) {
;             __builtin_amdgcn_fence(__ATOMIC_RELEASE, "agent");
;             asm volatile("s_waitcnt vmcnt(0)" ::: "memory");
;             const unsigned og = xb_add(sb + 2048, 1u);
;             if (og + 1u == nx) xb_add(sb + 2112, 1u);
;             else while (xb_ld(sb + 2112) == 0u) __builtin_amdgcn_s_sleep(1);
;             __builtin_amdgcn_fence(__ATOMIC_ACQUIRE, "agent");
;             xb_add(sb + 1024 + 64 * x, 1u);
;             asm volatile("s_waitcnt vmcnt(0)" ::: "memory");
;         } else {
;             while (xb_ld(sb + 1024 + 64 * x) == 0u) __builtin_amdgcn_s_sleep(1);
;             __builtin_amdgcn_fence(__ATOMIC_ACQUIRE, "agent");
;             asm volatile("s_waitcnt vmcnt(0)" ::: "memory");
;         }
;     }
;     __syncthreads();
; }
.LBB0_556:
	v_readlane_b32 s0, v254, 0
	v_readlane_b32 s1, v254, 1
	s_cmp_gt_i32 s1, 3
	s_cselect_b64 s[72:73], -1, 0
	s_and_b64 s[0:1], s[2:3], s[72:73]
	s_andn2_b64 vcc, exec, s[0:1]
	s_cbranch_vccnz .LBB0_585
	s_waitcnt vmcnt(0)
	s_waitcnt vmcnt(0) lgkmcnt(0)
	s_barrier
	s_mov_b64 s[74:75], exec
	v_readlane_b32 s0, v254, 2
	v_readlane_b32 s1, v254, 3
	s_and_b64 s[0:1], s[74:75], s[0:1]
	s_mov_b64 exec, s[0:1]
	s_cbranch_execz .LBB0_584
	s_cmp_lg_u32 s88, 0x100
	s_cbranch_scc1 .Lgb5_orig
	v_mov_b32_e32 v2, 0x23fc8
	ds_read_b32 v2, v2
	s_waitcnt vmcnt(0) lgkmcnt(0)
	v_readfirstlane_b32 s9, v2
	s_cmp_eq_u32 s9, 1
	s_cbranch_scc1 .Lgb5_norel
	buffer_wbl2 sc1
	s_waitcnt vmcnt(0)
.Lgb5_norel:
	v_readlane_b32 s4, v254, 6
	v_readlane_b32 s5, v254, 7
	s_and_b32 s0, s70, 7
	s_lshl_b32 s0, s0, 8
	s_add_i32 s0, s0, 0x114c0
	s_add_u32 s4, s4, s0
	s_addc_u32 s5, s5, 0
	s_lshr_b32 s6, s88, 3
	v_mov_b32_e32 v0, 0
	v_mov_b32_e32 v1, 1
	s_cmpk_gt_i32 s70, 0x7f
	s_cbranch_scc1 .Lgb5_spin
	global_atomic_add v0, v1, s[4:5]

; #define LAS __attribute__((address_space(3)))
; __device__ __forceinline__ unsigned xb_ld(unsigned* p) { return __hip_atomic_load(p, __ATOMIC_RELAXED, __HIP_MEMORY_SCOPE_AGENT); }
; __device__ __forceinline__ unsigned xb_add(unsigned* p, unsigned v) { return __hip_atomic_fetch_add(p, v, __ATOMIC_RELAXED, __HIP_MEMORY_SCOPE_AGENT); }
; __device__ __forceinline__ unsigned xb_xcc_id() { return (unsigned)__builtin_amdgcn_s_getreg((3 << 11) | 20) & 0xFu; }
; __device__ __forceinline__ void grid_barrier(unsigned* barw, int k, volatile LAS unsigned* st) {
;     asm volatile("s_waitcnt vmcnt(0)" ::: "memory");
;     __syncthreads();
;     if (threadIdx.x == 0) {
;         __builtin_amdgcn_s_waitcnt(0);
;         const unsigned x = xb_xcc_id();
;         unsigned nloc = st[0], nx = st[1];
;         if (nloc == 0u) {
;             const unsigned G = gridDim.x;
;             for (;;) { unsigned sum = 0u, cnt = 0u, mine = 0u;
; #pragma unroll
;                 for (unsigned j = 0; j < 16; ++j) { const unsigned c = xb_ld(barw + 64 * j); sum += c; cnt += (c > 0u) ? 1u : 0u; mine = (j == x) ? c : mine; }
;                 if (sum == G) { nloc = mine; nx = cnt; break; }
;                 __builtin_amdgcn_s_sleep(1); }
;             st[0] = nloc; st[1] = nx;
;         }
;         unsigned* sb = barw + 1024 + k * 2304;
;         const unsigned old = xb_add(sb + 64 * x, 1u);
;         if (old + 1u == nloc) {
;             __builtin_amdgcn_fence(__ATOMIC_RELEASE, "agent");
;             asm volatile("s_waitcnt vmcnt(0)" ::: "memory");
;             const unsigned og = xb_add(sb + 2048, 1u);
;             if (og + 1u == nx) xb_add(sb + 2112, 1u);
;             else while (xb_ld(sb + 2112) == 0u) __builtin_amdgcn_s_sleep(1);
;             __builtin_amdgcn_fence(__ATOMIC_ACQUIRE, "agent");
;             xb_add(sb + 1024 + 64 * x, 1u);
;             asm volatile("s_waitcnt vmcnt(0)" ::: "memory");
;         } else {
;             while (xb_ld(sb + 1024 + 64 * x) == 0u) __builtin_amdgcn_s_sleep(1);
;             __builtin_amdgcn_fence(__ATOMIC_ACQUIRE, "agent");
;             asm volatile("s_waitcnt vmcnt(0)" ::: "memory");
;         }
;     }
;     __syncthreads();
; }
.LBB0_680:
	v_readlane_b32 s0, v254, 0
	v_readlane_b32 s1, v254, 1
	s_cmp_gt_i32 s1, 4
	s_cselect_b64 s[72:73], -1, 0
	s_and_b64 s[0:1], s[8:9], s[72:73]
	s_andn2_b64 vcc, exec, s[0:1]
	s_cbranch_vccnz .LBB0_709
	s_waitcnt vmcnt(0)
	s_waitcnt vmcnt(0) lgkmcnt(0)
	s_barrier
	s_mov_b64 s[74:75], exec
	v_readlane_b32 s0, v254, 2
	v_readlane_b32 s1, v254, 3
	s_and_b64 s[0:1], s[74:75], s[0:1]
	s_mov_b64 exec, s[0:1]
	s_cbranch_execz .LBB0_708
	s_add_u32 s4, s78, 0x12f40
	s_addc_u32 s5, s79, 0
	v_mov_b32_e32 v0, 0
	v_mov_b32_e32 v1, 1
	global_atomic_add v0, v1, s[4:5]
	s_cmp_lg_u32 s88, 0x100
	s_cbranch_scc1 .Lgb3_orig
	s_waitcnt vmcnt(0) lgkmcnt(0)
	s_and_b32 s0, s70, 7
	s_lshl_b32 s0, s0, 8
	s_add_i32 s0, s0, 0x12400
	s_add_u32 s4, s78, s0
	s_addc_u32 s5, s79, 0
	s_lshr_b32 s6, s88, 3
	s_getreg_b32 s8, hwreg(HW_REG_XCC_ID, 0, 4)
	s_lshl_b32 s8, 1, s8
	v_mov_b32_e32 v0, 0
	v_mov_b32_e32 v1, s8
	global_atomic_or v2, v0, v1, s[4:5] offset:64 sc0
	s_waitcnt vmcnt(0)
	v_mov_b32_e32 v1, 1
	global_atomic_add v2, v0, v1, s[4:5] sc0
	s_waitcnt vmcnt(0)
	v_readfirstlane_b32 s7, v2
	s_add_i32 s7, s7, 1
	s_cmp_eq_u32 s7, s6
	s_cselect_b32 s9, 1, 0
	s_cmp_ge_u32 s7, s6
	s_cbranch_scc1 .Lgb3_all1

; #define LAS __attribute__((address_space(3)))
; __device__ __forceinline__ unsigned xb_ld(unsigned* p) { return __hip_atomic_load(p, __ATOMIC_RELAXED, __HIP_MEMORY_SCOPE_AGENT); }
; __device__ __forceinline__ unsigned xb_add(unsigned* p, unsigned v) { return __hip_atomic_fetch_add(p, v, __ATOMIC_RELAXED, __HIP_MEMORY_SCOPE_AGENT); }
; __device__ __forceinline__ unsigned xb_xcc_id() { return (unsigned)__builtin_amdgcn_s_getreg((3 << 11) | 20) & 0xFu; }
; __device__ __forceinline__ void grid_barrier(unsigned* barw, int k, volatile LAS unsigned* st) {
;     asm volatile("s_waitcnt vmcnt(0)" ::: "memory");
;     __syncthreads();
;     if (threadIdx.x == 0) {
;         __builtin_amdgcn_s_waitcnt(0);
;         const unsigned x = xb_xcc_id();
;         unsigned nloc = st[0], nx = st[1];
;         if (nloc == 0u) {
;             const unsigned G = gridDim.x;
;             for (;;) { unsigned sum = 0u, cnt = 0u, mine = 0u;
; #pragma unroll
;                 for (unsigned j = 0; j < 16; ++j) { const unsigned c = xb_ld(barw + 64 * j); sum += c; cnt += (c > 0u) ? 1u : 0u; mine = (j == x) ? c : mine; }
;                 if (sum == G) { nloc = mine; nx = cnt; break; }
;                 __builtin_amdgcn_s_sleep(1); }
;             st[0] = nloc; st[1] = nx;
;         }
;         unsigned* sb = barw + 1024 + k * 2304;
;         const unsigned old = xb_add(sb + 64 * x, 1u);
;         if (old + 1u == nloc) {
;             __builtin_amdgcn_fence(__ATOMIC_RELEASE, "agent");
;             asm volatile("s_waitcnt vmcnt(0)" ::: "memory");
;             const unsigned og = xb_add(sb + 2048, 1u);
;             if (og + 1u == nx) xb_add(sb + 2112, 1u);
;             else while (xb_ld(sb + 2112) == 0u) __builtin_amdgcn_s_sleep(1);
;             __builtin_amdgcn_fence(__ATOMIC_ACQUIRE, "agent");
;             xb_add(sb + 1024 + 64 * x, 1u);
;             asm volatile("s_waitcnt vmcnt(0)" ::: "memory");
;         } else {
;             while (xb_ld(sb + 1024 + 64 * x) == 0u) __builtin_amdgcn_s_sleep(1);
;             __builtin_amdgcn_fence(__ATOMIC_ACQUIRE, "agent");
;             asm volatile("s_waitcnt vmcnt(0)" ::: "memory");
;         }
;     }
;     __syncthreads();
; }
.Lgb3_all1:
	global_load_dword v2, v0, s[4:5] offset:64 sc1
	s_waitcnt vmcnt(0)
	v_readfirstlane_b32 s7, v2
	s_bcnt1_i32_b32 s7, s7
	s_cmp_eq_u32 s7, 1
	s_cbranch_scc1 .Lgb3_one
	buffer_wbl2 sc1
	s_waitcnt vmcnt(0)
	global_atomic_add v2, v0, v1, s[4:5] offset:128 sc0
	s_waitcnt vmcnt(0)
	v_readfirstlane_b32 s7, v2
	s_add_i32 s7, s7, 1
	s_cmp_eq_u32 s7, s6
	s_cselect_b32 s9, 1, 0
	s_cmp_ge_u32 s7, s6
	s_cbranch_scc1 .Lgb3_fl
.Lgb3_spin2:
	s_sleep 1
	global_load_dword v2, v0, s[4:5] offset:128 sc1
	s_waitcnt vmcnt(0)
	v_readfirstlane_b32 s7, v2
	s_cmp_lt_u32 s7, s6
	s_cbranch_scc1 .Lgb3_spin2
	s_branch .Lgb3_fl
.Lgb3_one:
	s_cmp_eq_u32 s9, 1
	s_cbranch_scc0 .Lgb3_acq
	buffer_wbl2 sc1
	s_waitcnt vmcnt(0)
.Lgb3_fl:
	s_cmp_eq_u32 s9, 1
	s_cbranch_scc0 .Lgb3_acq
	s_add_u32 s4, s78, 0x12c00
	s_addc_u32 s5, s79, 0
	global_atomic_add v0, v1, s[4:5]
	s_waitcnt vmcnt(0)

; #define LAS __attribute__((address_space(3)))
; __device__ __forceinline__ unsigned xb_ld(unsigned* p) { return __hip_atomic_load(p, __ATOMIC_RELAXED, __HIP_MEMORY_SCOPE_AGENT); }
; __device__ __forceinline__ unsigned xb_add(unsigned* p, unsigned v) { return __hip_atomic_fetch_add(p, v, __ATOMIC_RELAXED, __HIP_MEMORY_SCOPE_AGENT); }
; __device__ __forceinline__ unsigned xb_xcc_id() { return (unsigned)__builtin_amdgcn_s_getreg((3 << 11) | 20) & 0xFu; }
; __device__ __forceinline__ void grid_barrier(unsigned* barw, int k, volatile LAS unsigned* st) {
;     asm volatile("s_waitcnt vmcnt(0)" ::: "memory");
;     __syncthreads();
;     if (threadIdx.x == 0) {
;         __builtin_amdgcn_s_waitcnt(0);
;         const unsigned x = xb_xcc_id();
;         unsigned nloc = st[0], nx = st[1];
;         if (nloc == 0u) {
;             const unsigned G = gridDim.x;
;             for (;;) { unsigned sum = 0u, cnt = 0u, mine = 0u;
; #pragma unroll
;                 for (unsigned j = 0; j < 16; ++j) { const unsigned c = xb_ld(barw + 64 * j); sum += c; cnt += (c > 0u) ? 1u : 0u; mine = (j == x) ? c : mine; }
;                 if (sum == G) { nloc = mine; nx = cnt; break; }
;                 __builtin_amdgcn_s_sleep(1); }
;             st[0] = nloc; st[1] = nx;
;         }
;         unsigned* sb = barw + 1024 + k * 2304;
;         const unsigned old = xb_add(sb + 64 * x, 1u);
;         if (old + 1u == nloc) {
;             __builtin_amdgcn_fence(__ATOMIC_RELEASE, "agent");
;             asm volatile("s_waitcnt vmcnt(0)" ::: "memory");
;             const unsigned og = xb_add(sb + 2048, 1u);
;             if (og + 1u == nx) xb_add(sb + 2112, 1u);
;             else while (xb_ld(sb + 2112) == 0u) __builtin_amdgcn_s_sleep(1);
;             __builtin_amdgcn_fence(__ATOMIC_ACQUIRE, "agent");
;             xb_add(sb + 1024 + 64 * x, 1u);
;             asm volatile("s_waitcnt vmcnt(0)" ::: "memory");
;         } else {
;             while (xb_ld(sb + 1024 + 64 * x) == 0u) __builtin_amdgcn_s_sleep(1);
;             __builtin_amdgcn_fence(__ATOMIC_ACQUIRE, "agent");
;             asm volatile("s_waitcnt vmcnt(0)" ::: "memory");
;         }
;     }
;     __syncthreads();
; }
.Lgb2_acq:
	s_add_u32 s4, s78, 0x12c00
	s_addc_u32 s5, s79, 0
.Lgb2_pf:
	global_load_dword v2, v0, s[4:5] sc1
	s_waitcnt vmcnt(0)
	v_readfirstlane_b32 s7, v2
	s_cmp_ge_u32 s7, 8
	s_cbranch_scc1 .Lgb2_pfok
	s_sleep 1
	s_branch .Lgb2_pf
